# SSM B.u moved to f32 MFMA 4x4x1 (bit-identical) + scalar-fma scan; next-chunk load wait deferred; ph0 grid.sync replaced by XCD barrier
# speedup vs baseline: 1.0190x; 1.0190x over previous
; #define LAS __attribute__((address_space(3)))
; __device__ __forceinline__ unsigned xb_ld(unsigned* p)              { return __hip_atomic_load(p, __ATOMIC_RELAXED, __HIP_MEMORY_SCOPE_AGENT); }
; __device__ __forceinline__ unsigned xb_add(unsigned* p, unsigned v) { return __hip_atomic_fetch_add(p, v, __ATOMIC_RELAXED, __HIP_MEMORY_SCOPE_AGENT); }
; __device__ __forceinline__ unsigned xb_xcc_id() { return (unsigned)__builtin_amdgcn_s_getreg((3 << 11) | 20) & 0xFu; }
; __device__ __forceinline__ XcdBarrier xcd_barrier_post(unsigned* bar, volatile LAS unsigned* st) {
;     XcdBarrier b; b.bar = bar; b.x = xb_xcc_id(); b.st = st;
;     if (threadIdx.x == 0) (void)xb_add(&bar[XB_XCNT(b.x)], 1u);
;     return b;
; }
; __device__ __forceinline__ void xcd_barrier_complete(unsigned* bar, unsigned x, unsigned& nloc, unsigned& nx) {
;     const unsigned G = gridDim.x * gridDim.y * gridDim.z;
;     unsigned sum, cnt, mine, sp = 0u;
;     for (;;) {
;         sum = 0u; cnt = 0u; mine = 0u;
; #pragma unroll
;         for (unsigned j = 0; j < 16; ++j) { const unsigned c = xb_ld(&bar[XB_XCNT(j)]); sum += c; cnt += (c > 0u) ? 1u : 0u; mine = (j == x) ? c : mine; }
;         if (sum == G) break;
;         __builtin_amdgcn_s_sleep(1);
;         if ((++sp & 255u) == 0u) { if (xb_ld(&bar[XB_TMO])) break; if (sp > XB_SPIN_CAP) { atomicAdd(&bar[XB_TMO], 1u); break; } }
;     }
;     nloc = mine > 0u ? mine : 1u; nx = cnt > 0u ? cnt : 1u;
; }
;     __device__ __forceinline__ bool next(int i, Unit& u) const {
;         const long L = (long)i * G + c; if (L >= nwg) return false;
;         tile((int)L, u); return true;
;     }
;     __device__ __forceinline__ void init(int K, int nsl_, int G_, int c_) { base.init(MP, DM, K, G_, c_); G = G_; c = c_; nkt = K / BK; nsl = nsl_; }
;     __device__ __forceinline__ bool next(int i, Unit& u) const {
;         const long L = (long)i * G + c; if (L >= 256 + 16 * nsl) return false;
;         const bool full = L < 256;
;         const int sidx = (int)L - 256, t = sidx / nsl, sl = sidx - t * nsl, q = nkt / nsl;
;         Unit b; base.tile(full ? (int)L : 0, b);
;         const int pm = full ? b.pm : 32 + (t >> 3), pn = full ? b.pn : (t & 7), kt0 = full ? 0 : sl * q, nk = full ? nkt : q, sli = full ? -1 : sl;
;         u.pm = pm; u.pn = pn; u.kt0 = kt0; u.nkt = nk; u.slice = sli; return true;
.LBB0_13:
	s_add_i32 s3, s2, 0xffffff00
	v_writelane_b32 v251, s3, 5
	s_cmp_lt_u32 s3, 64
	s_cselect_b32 s15, s3, s2
	s_add_i32 s4, s2, 0x100
	s_cmp_lt_u32 s2, 64
	s_cselect_b32 s15, s4, s15
	s_add_i32 s3, s15, 0xffffff00
	s_ashr_i32 s4, s3, 31
	s_lshr_b32 s4, s4, 30
	s_add_i32 s4, s3, s4
	s_cmpk_lt_i32 s15, 0x100
	s_cselect_b32 s5, s15, 0
	s_ashr_i32 s6, s5, 31
	s_lshr_b32 s6, s6, 29
	s_add_i32 s6, s5, s6
	s_ashr_i32 s7, s6, 3
	s_and_b32 s6, s6, -8
	s_sub_i32 s5, s5, s6
	s_lshl_b32 s6, s5, 5
	s_bfe_u32 s8, s4, 0x30002
	s_cmp_lt_i32 s5, 0
	s_mul_i32 s5, s5, 33
	s_cselect_b32 s5, s5, s6
	s_add_i32 s5, s5, s7
	s_ashr_i32 s6, s5, 31
	s_lshr_b32 s6, s6, 27
	s_add_i32 s6, s5, s6
	s_and_b32 s7, s6, 0xffe0
	s_sub_i32 s5, s5, s7
	s_bfe_i32 s7, s5, 0x80000
	s_bfe_u32 s7, s7, 0x2000d
	s_add_i32 s7, s5, s7
	s_bfe_i32 s9, s7, 0x80000
	s_sext_i32_i16 s9, s9
	s_ashr_i32 s9, s9, 2
	s_cmpk_lt_i32 s15, 0x100
	s_cselect_b32 s14, s9, s8
	s_and_b32 s7, s7, 0xfc
	s_ashr_i32 s6, s6, 5
	s_sub_i32 s5, s5, s7
	s_ashr_i32 s8, s4, 5
	s_lshl_b32 s6, s6, 2
	s_sext_i32_i8 s5, s5
	s_add_i32 s8, s8, 32
	s_add_i32 s6, s6, s5
	s_cmpk_lt_i32 s15, 0x100
	s_cselect_b32 s16, s6, s8
	s_and_b32 s4, s4, -4
	s_sub_i32 s4, s3, s4
	s_lshl_b32 s5, s4, 3
	s_cmpk_lt_i32 s15, 0x100
	s_cselect_b32 s3, -1, s4
	v_writelane_b32 v251, s3, 6
	s_cselect_b32 s3, 0x58, 22
	s_mul_i32 s4, s4, 22
	v_writelane_b32 v251, s3, 7
	s_cselect_b32 s4, 0, s4
	s_cselect_b32 s3, 32, 8
	s_cselect_b32 s6, 0, s5
	s_cmpk_lt_i32 s2, 0x500
	v_writelane_b32 v251, s3, 8
	s_cselect_b64 s[8:9], -1, 0
	v_writelane_b32 v251, s8, 9
	s_cmpk_lt_i32 s2, 0x154
	v_mov_b32_e32 v179, 0x358637bd
	v_writelane_b32 v251, s9, 10
	s_cselect_b64 s[8:9], -1, 0
	s_ashr_i32 s3, s2, 31
	s_lshr_b32 s5, s3, 29
	v_writelane_b32 v251, s8, 11
	s_add_i32 s5, s2, s5
	v_mov_b32_e32 v180, 0x260
	v_writelane_b32 v251, s9, 12
	s_ashr_i32 s8, s5, 3
	s_and_b32 s5, s5, -8
	s_sub_i32 s9, s2, s5
	s_mul_i32 s5, s9, 42
	v_writelane_b32 v251, s3, 13
	s_add_i32 s10, s5, 4
	s_ashr_i32 s3, s56, 31
	s_cmpk_lt_i32 s2, 0x140
	v_writelane_b32 v251, s3, 14
	s_cselect_b64 s[18:19], -1, 0
	v_writelane_b32 v251, s18, 15
	s_ashr_i32 s5, s4, 31
	s_lshl_b64 s[4:5], s[4:5], 7
	v_writelane_b32 v251, s19, 16
	v_writelane_b32 v251, s4, 17
	s_cmpk_lt_i32 s2, 0x5d8
	v_mov_b32_e32 v149, 0
	v_writelane_b32 v251, s5, 18
	v_writelane_b32 v251, s2, 19
	s_cselect_b64 s[2:3], -1, 0
	v_writelane_b32 v251, s2, 20
	s_ashr_i32 s7, s6, 31
	v_mov_b32_e32 v181, 0x3c0881c4
	v_writelane_b32 v251, s3, 21
	s_lshl_b64 s[2:3], s[6:7], 7
	v_writelane_b32 v251, s2, 22
	v_mov_b32_e32 v182, 0xbab64f3b
	v_mov_b32_e32 v183, 1
	v_writelane_b32 v251, s3, 23
	s_add_u32 s2, s0, 0x15100200
	s_addc_u32 s3, s1, 0
	s_add_u32 s22, s0, 0x15100400
	s_addc_u32 s23, s1, 0
	s_add_u32 s24, s0, 0x15100500
	s_addc_u32 s25, s1, 0
	s_add_u32 s26, s0, 0x15100600
	s_addc_u32 s27, s1, 0
	s_add_u32 s28, s0, 0x15100700
	v_writelane_b32 v251, s2, 24
	s_addc_u32 s29, s1, 0
	v_mov_b32_e32 v192, 0x7f800000
	v_writelane_b32 v251, s3, 25
	s_add_u32 s2, s0, 0x15100800
	s_addc_u32 s3, s1, 0
	v_writelane_b32 v251, s2, 26
	v_not_b32_e32 v194, 31
	v_mov_b32_e32 v195, 0x7fc00000
	v_writelane_b32 v251, s3, 27
	s_add_u32 s2, s0, 0x15100900
	s_addc_u32 s3, s1, 0
	v_writelane_b32 v251, s2, 28
	v_mov_b32_e32 v196, 0x42800000
	v_mov_b32_e32 v197, 0xf149f2ca
	v_writelane_b32 v251, s3, 29
	s_add_u32 s2, s0, 0x15100a00
	s_addc_u32 s3, s1, 0
	v_writelane_b32 v251, s2, 30
	v_mov_b64_e32 v[150:151], 0x140
	v_mov_b64_e32 v[152:153], 0x13f
	v_writelane_b32 v251, s3, 31
	s_add_u32 s2, s0, 0x15100b00
	s_addc_u32 s3, s1, 0
	v_writelane_b32 v251, s2, 32
	v_mov_b64_e32 v[154:155], 0x100
	v_mov_b64_e32 v[156:157], 0x5d7
	v_writelane_b32 v251, s3, 33
	s_add_u32 s2, s0, 0x15100c00
	s_addc_u32 s3, s1, 0
	v_writelane_b32 v251, s2, 34
	v_mov_b64_e32 v[158:159], 0x5d8
	s_movk_i32 s80, 0x7f
	v_writelane_b32 v251, s3, 35
	s_add_u32 s2, s0, 0x15100d00
	s_addc_u32 s3, s1, 0
	v_writelane_b32 v251, s2, 36
	s_mov_b32 s83, 0
	s_mov_b64 s[18:19], 0x80
	v_writelane_b32 v251, s3, 37
	s_add_u32 s2, s0, 0x15100e00
	s_addc_u32 s3, s1, 0
	v_writelane_b32 v251, s2, 38
	s_nop 1
	v_writelane_b32 v251, s3, 39
	s_add_u32 s2, s0, 0x15100f00
	s_addc_u32 s3, s1, 0
	v_writelane_b32 v251, s2, 40
	s_nop 1
	v_writelane_b32 v251, s3, 41
	s_add_u32 s2, s0, 0x15101000
	s_addc_u32 s3, s1, 0
	v_writelane_b32 v251, s2, 42
	s_nop 1
	v_writelane_b32 v251, s3, 43
	s_add_u32 s2, s0, 0x15101100
	s_addc_u32 s3, s1, 0
	v_writelane_b32 v251, s2, 44
	s_nop 1
	v_writelane_b32 v251, s3, 45
	s_add_u32 s2, s0, 0x15101200
	s_addc_u32 s3, s1, 0
	v_writelane_b32 v251, s2, 46
	s_nop 1
	v_writelane_b32 v251, s3, 47
	s_add_u32 s2, s0, 0x15101300
	s_addc_u32 s3, s1, 0
	v_writelane_b32 v251, s2, 48
	s_cmp_eq_u32 s12, 15
	s_nop 0
	v_writelane_b32 v251, s3, 49
	s_cselect_b64 s[2:3], -1, 0
	v_writelane_b32 v251, s2, 50
	s_cmp_eq_u32 s12, 14
	s_nop 0
	v_writelane_b32 v251, s3, 51
	s_cselect_b64 s[2:3], -1, 0
	v_writelane_b32 v251, s2, 52
	s_cmp_eq_u32 s12, 13
	s_nop 0
	v_writelane_b32 v251, s3, 53
	s_cselect_b64 s[2:3], -1, 0
	v_writelane_b32 v251, s2, 54
	s_cmp_eq_u32 s12, 12
	s_nop 0
	v_writelane_b32 v251, s3, 55
	s_cselect_b64 s[2:3], -1, 0
	v_writelane_b32 v251, s2, 56
	s_cmp_eq_u32 s12, 11
	s_nop 0
	v_writelane_b32 v251, s3, 57
	s_cselect_b64 s[2:3], -1, 0
	v_writelane_b32 v251, s2, 58
	s_cmp_eq_u32 s12, 10
	s_nop 0
	v_writelane_b32 v251, s3, 59
	s_cselect_b64 s[2:3], -1, 0
	v_writelane_b32 v251, s2, 60
	s_cmp_eq_u32 s12, 9
	s_nop 0
	v_writelane_b32 v251, s3, 61
	s_cselect_b64 s[2:3], -1, 0
	v_writelane_b32 v251, s2, 62
	s_cmp_eq_u32 s12, 8
	s_nop 0
	v_writelane_b32 v251, s3, 63
	s_cselect_b64 s[2:3], -1, 0
; __device__ __forceinline__ unsigned xb_ld(unsigned* p)              { return __hip_atomic_load(p, __ATOMIC_RELAXED, __HIP_MEMORY_SCOPE_AGENT); }
; __device__ __forceinline__ void xcd_barrier_complete(unsigned* bar, unsigned x, unsigned& nloc, unsigned& nx) {
;     const unsigned G = gridDim.x * gridDim.y * gridDim.z;
;     unsigned sum, cnt, mine, sp = 0u;
;     for (;;) {
;         sum = 0u; cnt = 0u; mine = 0u;
; #pragma unroll
;         for (unsigned j = 0; j < 16; ++j) { const unsigned c = xb_ld(&bar[XB_XCNT(j)]); sum += c; cnt += (c > 0u) ? 1u : 0u; mine = (j == x) ? c : mine; }
;         if (sum == G) break;
;         __builtin_amdgcn_s_sleep(1);
;         if ((++sp & 255u) == 0u) { if (xb_ld(&bar[XB_TMO])) break; if (sp > XB_SPIN_CAP) { atomicAdd(&bar[XB_TMO], 1u); break; } }
;     }
;     nloc = mine > 0u ? mine : 1u; nx = cnt > 0u ? cnt : 1u;
; }
; __global__ void __launch_bounds__(512, 2) fwd(Args a_unused) {
;     ...
;         if (ph == 0) grid.sync();
;         else xcd_barrier(xbar);
	v_writelane_b32 v252, s2, 0
	s_cmp_eq_u32 s12, 7
	s_nop 0
	v_writelane_b32 v252, s3, 1
	s_cselect_b64 s[2:3], -1, 0
	v_writelane_b32 v252, s2, 2
	s_cmp_eq_u32 s12, 6
	s_nop 0
	v_writelane_b32 v252, s3, 3
	s_cselect_b64 s[2:3], -1, 0
	v_writelane_b32 v252, s2, 4
	s_cmp_eq_u32 s12, 5
	s_nop 0
	v_writelane_b32 v252, s3, 5
	s_cselect_b64 s[2:3], -1, 0
	v_writelane_b32 v252, s2, 6
	s_cmp_eq_u32 s12, 4
	s_nop 0
	v_writelane_b32 v252, s3, 7
	s_cselect_b64 s[2:3], -1, 0
	v_writelane_b32 v252, s2, 8
	s_cmp_eq_u32 s12, 3
	s_nop 0
	v_writelane_b32 v252, s3, 9
	s_cselect_b64 s[2:3], -1, 0
	v_writelane_b32 v252, s2, 10
	s_cmp_eq_u32 s12, 2
	s_nop 0
	v_writelane_b32 v252, s3, 11
	s_cselect_b64 s[2:3], -1, 0
	v_writelane_b32 v252, s2, 12
	s_cmp_eq_u32 s12, 1
	s_nop 0
	v_writelane_b32 v252, s3, 13
	s_cselect_b64 s[2:3], -1, 0
	v_writelane_b32 v252, s2, 14
	s_cmp_eq_u32 s12, 0
	s_nop 0
	v_writelane_b32 v252, s3, 15
	s_cselect_b64 s[2:3], -1, 0
	v_writelane_b32 v252, s2, 16
	s_lshl_b32 s4, s12, 8
	s_nop 0
	v_writelane_b32 v252, s3, 17
	s_add_u32 s2, s54, s4
	s_addc_u32 s3, s55, 0
	s_add_u32 s4, s2, 0x1400
	s_addc_u32 s5, s3, 0
	v_writelane_b32 v252, s4, 18
	s_add_u32 s2, s2, 0x2400
	s_addc_u32 s3, s3, 0
	v_writelane_b32 v252, s5, 19
	v_writelane_b32 v252, s2, 20
	s_nop 1
	v_writelane_b32 v252, s3, 21
	s_add_u32 s2, s0, 0x15103400
	s_addc_u32 s3, s1, 0
	v_writelane_b32 v252, s2, 22
	s_add_u32 s0, s0, 0x15103500
	s_addc_u32 s1, s1, 0
	v_writelane_b32 v252, s3, 23
	v_writelane_b32 v252, s0, 24
	s_cmp_lt_i32 s9, 4
	s_nop 0
	v_writelane_b32 v252, s1, 25
	s_mul_i32 s0, s9, 43
	s_cselect_b32 s0, s0, s10
	s_add_i32 s0, s0, s8
	s_mul_hi_i32 s1, s0, 0x66666667
	s_lshr_b32 s2, s1, 31
	s_ashr_i32 s1, s1, 4
	s_add_i32 s1, s1, s2
	s_mul_i32 s2, s1, 40
	s_lshl_b32 s3, s1, 2
	s_sub_i32 s2, s0, s2
	s_sub_i32 s0, 34, s3
	s_min_u32 s4, s0, 4
	s_mul_i32 s0, s14, 0x2c0000
	s_ashr_i32 s17, s16, 31
	v_writelane_b32 v252, s0, 26
	s_ashr_i32 s0, s0, 31
	v_writelane_b32 v252, s0, 27
	s_cmp_lt_i32 s9, 0
	s_movk_i32 s0, 0xbc
	s_cselect_b32 s0, s0, 0xbb
	s_mul_i32 s0, s9, s0
	s_add_i32 s0, s0, s8
	s_mul_hi_i32 s1, s0, 0x2e8ba2e9
	s_lshr_b32 s5, s1, 31
	s_ashr_i32 s1, s1, 5
	s_add_i32 s1, s1, s5
	s_mul_i32 s5, s1, 0xb0
	s_lshl_b32 s6, s1, 2
	s_sub_i32 s5, s0, s5
	s_sub_i32 s0, 34, s6
	s_min_u32 s7, s0, 4
	s_ashr_i32 s0, s2, 30
	v_cvt_f32_ubyte0_e32 v2, s4
	s_or_b32 s8, s0, 1
	s_mov_b32 s0, s16
	v_cvt_f32_i32_e32 v1, s2
	v_rcp_iflag_f32_e32 v3, v2
	v_writelane_b32 v252, s0, 28
	s_ashr_i32 s15, s14, 31
	v_mul_f32_e32 v3, v1, v3
	v_writelane_b32 v252, s1, 29
	s_lshl_b64 s[0:1], s[16:17], 20
	v_writelane_b32 v252, s0, 30
	v_trunc_f32_e32 v3, v3
	v_fma_f32 v1, -v3, v2, v1
	v_writelane_b32 v252, s1, 31
	s_mov_b32 s0, s14
	v_writelane_b32 v252, s0, 32
	s_nop 1
	v_writelane_b32 v252, s1, 33
	s_lshl_b64 s[0:1], s[14:15], 20
	v_writelane_b32 v252, s0, 34
	s_nop 1
	v_writelane_b32 v252, s1, 35
	v_cmp_ge_f32_e64 s[0:1], |v1|, v2
	v_cvt_i32_f32_e32 v1, v3
	s_and_b64 s[0:1], s[0:1], exec
	s_cselect_b32 s0, s8, 0
	v_cvt_f32_ubyte0_e32 v2, s7
	v_readfirstlane_b32 s1, v1
	s_add_i32 s0, s1, s0
	s_mul_i32 s1, s0, s4
	s_sub_i32 s1, s2, s1
	s_sext_i32_i8 s1, s1
	s_add_i32 s8, s3, s1
	v_cvt_f32_i32_e32 v1, s5
	v_rcp_iflag_f32_e32 v3, v2
	s_bfe_i64 s[2:3], s[0:1], 0x80000
	s_lshl_b64 s[2:3], s[2:3], 20
	v_writelane_b32 v252, s2, 36
	s_ashr_i32 s9, s8, 31
	v_mul_f32_e32 v3, v1, v3
	v_writelane_b32 v252, s3, 37
	s_mov_b32 s2, s8
	v_writelane_b32 v252, s2, 38
	v_trunc_f32_e32 v3, v3
	s_ashr_i32 s1, s5, 30
	v_writelane_b32 v252, s3, 39
	s_lshl_b64 s[2:3], s[8:9], 20
	v_fma_f32 v1, -v3, v2, v1
	v_writelane_b32 v252, s2, 40
	s_or_b32 s1, s1, 1
	s_sext_i32_i8 s0, s0
	v_writelane_b32 v252, s3, 41
	v_cmp_ge_f32_e64 s[2:3], |v1|, v2
	s_and_b64 s[2:3], s[2:3], exec
	s_mov_b32 s2, s56
	v_writelane_b32 v252, s2, 42
	v_lshrrev_b32_e32 v1, 20, v0
	v_lshrrev_b32_e32 v0, 10, v0
	v_writelane_b32 v252, s3, 43
	s_load_dword s3, s[20:21], 0x110
	v_or_b32_e32 v0, v0, v1
	v_cvt_i32_f32_e32 v1, v3
	s_mul_i32 s2, s57, s56
	s_movk_i32 s56, 0x1400
	s_waitcnt lgkmcnt(0)
	s_mul_i32 s2, s2, s3
	v_writelane_b32 v252, s2, 44
	v_writelane_b32 v252, s0, 45
	s_cselect_b32 s0, s1, 0
	v_readfirstlane_b32 s1, v1
	s_add_i32 s0, s1, s0
	s_mul_i32 s1, s0, s7
	s_sub_i32 s1, s5, s1
	s_movk_i32 s2, 0x3ff
	s_sext_i32_i16 s1, s1
	v_and_or_b32 v0, v0, s2, v178
	s_add_i32 s2, s6, s1
	s_sext_i32_i16 s1, s0
	v_writelane_b32 v252, s1, 46
	s_bfe_i64 s[0:1], s[0:1], 0x100000
	s_lshl_b64 s[0:1], s[0:1], 20
	v_writelane_b32 v252, s0, 47
	s_ashr_i32 s3, s2, 31
	s_ashr_i32 s51, s50, 31
	v_writelane_b32 v252, s1, 48
	s_add_i32 s0, 0, 0x11880
	v_writelane_b32 v252, s0, 49
	s_add_i32 s0, 0, 0x12880
	v_writelane_b32 v252, s0, 50
	s_add_i32 s0, 0, 0x20010
	v_writelane_b32 v252, s0, 51
	s_add_i32 s0, 0, 0x20004
	v_writelane_b32 v252, s0, 52
	s_mov_b32 s0, 0
	v_writelane_b32 v252, s0, 53
	v_cmp_eq_u32_e64 s[0:1], 0, v0
	v_mbcnt_lo_u32_b32 v1, -1, 0
	s_nop 0
	v_writelane_b32 v252, s0, 54
	v_mbcnt_hi_u32_b32 v184, -1, v1
	v_and_b32_e32 v1, 64, v184
	v_writelane_b32 v252, s1, 55
	s_mov_b32 s0, s2
	v_writelane_b32 v252, s0, 56
	v_add_u32_e32 v185, 64, v1
	v_xor_b32_e32 v186, 1, v184
	v_writelane_b32 v252, s1, 57
	s_lshl_b64 s[0:1], s[2:3], 20
	v_writelane_b32 v252, s0, 58
	v_xor_b32_e32 v193, 8, v184
	v_xor_b32_e32 v187, 16, v184
	v_writelane_b32 v252, s1, 59
	s_lshl_b64 s[0:1], s[50:51], 13
	v_writelane_b32 v252, s0, 60
	v_xor_b32_e32 v250, 32, v184
	s_nop 0
	v_writelane_b32 v252, s1, 61
	s_mov_b32 s0, s50
	v_writelane_b32 v252, s0, 62
	s_nop 1
	v_writelane_b32 v252, s1, 63
	s_lshl_b64 s[0:1], s[50:51], 12
	v_writelane_b32 v253, s0, 0
	s_nop 1
	v_writelane_b32 v253, s1, 1
	v_writelane_b32 v253, s20, 2
	s_nop 1
	v_writelane_b32 v253, s21, 3
	v_writelane_b32 v253, s22, 4
	s_nop 1
	v_writelane_b32 v253, s23, 5
	v_writelane_b32 v253, s24, 6
	s_nop 1
	v_writelane_b32 v253, s25, 7
	v_writelane_b32 v253, s26, 8
	s_nop 1
	v_writelane_b32 v253, s27, 9
	v_writelane_b32 v253, s28, 10
	s_nop 1
	v_writelane_b32 v253, s29, 11
	s_branch .LBB0_17
.LBB0_16:
	v_readlane_b32 s0, v252, 53
	s_add_i32 s0, s0, 1
	s_cmp_eq_u32 s0, 22
	v_writelane_b32 v252, s0, 53
	s_waitcnt lgkmcnt(0)
	s_cbranch_scc1 .LBB0_395

; #define LAS __attribute__((address_space(3)))
; template <bool SAMPLE>
; __device__ __forceinline__ void ssm_item(kp_t kp, LAS unsigned char* lds, int l, int item, const bf16_t* Z, float* YM, int tid, int lane, int wave) {
;     ...
;         f32x2 hl[16]; f32x2 h = (f32x2){0.f, 0.f};
; #pragma unroll
;         for (int tt = 0; tt < 16; ++tt) { const LAS f32x4* up = (const LAS f32x4*)(U + (wave * 16 + tt) * 16);
;             if (SAMPLE && (tt & 3) == 0) h = h0[tt >> 2];
;             f32x2 bu = (f32x2){0.f, 0.f};
; #pragma unroll
;             for (int q = 0; q < 4; ++q) { const f32x4 u = up[q];
; #pragma unroll
;                 for (int e = 0; e < 4; ++e) bu = __builtin_elementwise_fma(B2[4 * q + e], (f32x2){u[e], u[e]}, bu); }
;             const f32x2 t1 = __builtin_elementwise_fma((f32x2){lr, lr}, h, bu);
;             h = __builtin_elementwise_fma((f32x2){-li, li}, (f32x2){h.y, h.x}, t1); hl[tt] = h;
.LBB0_100:
	s_add_i32 s25, s3, s24
	v_and_b32_e32 v254, 3, v184
	v_lshl_add_u32 v254, v254, 6, s25
	s_waitcnt lgkmcnt(0)
	s_barrier
	ds_read_b128 v[20:23], v254
	ds_read_b64 v[244:245], v254 offset:16
	ds_read_b64 v[248:249], v254 offset:24
	ds_read_b128 v[174:177], v254 offset:32
	ds_read_b128 v[188:191], v254 offset:48
	v_cndmask_b32_e64 v247, 0, v133, s[0:1]
	v_mul_f32_e32 v246, v107, v133
	s_waitcnt lgkmcnt(2)
	v_mfma_f32_4x4x1_16b_f32 v[232:235], v20, v72, 0
	v_mfma_f32_4x4x1_16b_f32 v[236:239], v20, v73, 0
	s_nop 0
	v_mfma_f32_4x4x1_16b_f32 v[232:235], v21, v64, v[232:235]
	v_mfma_f32_4x4x1_16b_f32 v[236:239], v21, v65, v[236:239]
	s_nop 0
	v_mfma_f32_4x4x1_16b_f32 v[232:235], v22, v60, v[232:235]
	v_mfma_f32_4x4x1_16b_f32 v[236:239], v22, v61, v[236:239]
	s_nop 0
	v_mfma_f32_4x4x1_16b_f32 v[232:235], v23, v62, v[232:235]
	v_mfma_f32_4x4x1_16b_f32 v[236:239], v23, v63, v[236:239]
	s_nop 0
	v_mfma_f32_4x4x1_16b_f32 v[232:235], v244, v66, v[232:235]
	v_mfma_f32_4x4x1_16b_f32 v[236:239], v244, v67, v[236:239]
	s_nop 0
	v_mfma_f32_4x4x1_16b_f32 v[232:235], v245, v52, v[232:235]
	v_mfma_f32_4x4x1_16b_f32 v[236:239], v245, v53, v[236:239]
	s_nop 0
	v_mfma_f32_4x4x1_16b_f32 v[232:235], v248, v56, v[232:235]
	v_mfma_f32_4x4x1_16b_f32 v[236:239], v248, v57, v[236:239]
	s_nop 0
	v_mfma_f32_4x4x1_16b_f32 v[232:235], v249, v54, v[232:235]
	v_mfma_f32_4x4x1_16b_f32 v[236:239], v249, v55, v[236:239]
	s_nop 0
	ds_read_b128 v[20:23], v254 offset:256
	ds_read_b64 v[244:245], v254 offset:272
	ds_read_b64 v[248:249], v254 offset:280
	s_waitcnt lgkmcnt(3)
	v_mfma_f32_4x4x1_16b_f32 v[232:235], v174, v58, v[232:235]
	v_mfma_f32_4x4x1_16b_f32 v[236:239], v174, v59, v[236:239]
	s_nop 0
	v_mfma_f32_4x4x1_16b_f32 v[232:235], v175, v44, v[232:235]
	v_mfma_f32_4x4x1_16b_f32 v[236:239], v175, v45, v[236:239]
	s_nop 0
	v_mfma_f32_4x4x1_16b_f32 v[232:235], v176, v48, v[232:235]
	v_mfma_f32_4x4x1_16b_f32 v[236:239], v176, v49, v[236:239]
	s_nop 0
	v_mfma_f32_4x4x1_16b_f32 v[232:235], v177, v46, v[232:235]
	v_mfma_f32_4x4x1_16b_f32 v[236:239], v177, v47, v[236:239]
	s_nop 0
	v_mfma_f32_4x4x1_16b_f32 v[232:235], v188, v50, v[232:235]
	v_mfma_f32_4x4x1_16b_f32 v[236:239], v188, v51, v[236:239]
	s_nop 0
	v_mfma_f32_4x4x1_16b_f32 v[232:235], v189, v36, v[232:235]
	v_mfma_f32_4x4x1_16b_f32 v[236:239], v189, v37, v[236:239]
	s_nop 0
	v_mfma_f32_4x4x1_16b_f32 v[232:235], v190, v40, v[232:235]
	v_mfma_f32_4x4x1_16b_f32 v[236:239], v190, v41, v[236:239]
	s_nop 0
	v_mfma_f32_4x4x1_16b_f32 v[232:235], v191, v38, v[232:235]
	v_mfma_f32_4x4x1_16b_f32 v[236:239], v191, v39, v[236:239]
	s_nop 0
	ds_read_b128 v[174:177], v254 offset:288
	ds_read_b128 v[188:191], v254 offset:304
	s_nop 4
	v_fma_f32 v138, v42, 0, v232
	v_fma_f32 v139, v43, 0, v236
	v_fma_f32 v138, v70, 0, v138
	v_fma_f32 v139, v71, 0, v139
	v_fma_f32 v140, v42, v138, v233
	v_fma_f32 v141, v43, v139, v237
	v_fma_f32 v140, v70, v139, v140
	v_fma_f32 v141, v71, v138, v141
	v_fma_f32 v142, v42, v140, v234
	v_fma_f32 v143, v43, v141, v238
	v_fma_f32 v142, v70, v141, v142
	v_fma_f32 v143, v71, v140, v143
	v_fma_f32 v144, v42, v142, v235
	v_fma_f32 v145, v43, v143, v239
	v_fma_f32 v144, v70, v143, v144
	v_fma_f32 v145, v71, v142, v145
	s_waitcnt lgkmcnt(2)
	v_mfma_f32_4x4x1_16b_f32 v[232:235], v20, v72, 0
	v_mfma_f32_4x4x1_16b_f32 v[236:239], v20, v73, 0
	s_nop 0
	v_mfma_f32_4x4x1_16b_f32 v[232:235], v21, v64, v[232:235]
	v_mfma_f32_4x4x1_16b_f32 v[236:239], v21, v65, v[236:239]
	s_nop 0
	v_mfma_f32_4x4x1_16b_f32 v[232:235], v22, v60, v[232:235]
	v_mfma_f32_4x4x1_16b_f32 v[236:239], v22, v61, v[236:239]
	s_nop 0
	v_mfma_f32_4x4x1_16b_f32 v[232:235], v23, v62, v[232:235]
	v_mfma_f32_4x4x1_16b_f32 v[236:239], v23, v63, v[236:239]
	s_nop 0
	v_mfma_f32_4x4x1_16b_f32 v[232:235], v244, v66, v[232:235]
	v_mfma_f32_4x4x1_16b_f32 v[236:239], v244, v67, v[236:239]
	s_nop 0
	v_mfma_f32_4x4x1_16b_f32 v[232:235], v245, v52, v[232:235]
	v_mfma_f32_4x4x1_16b_f32 v[236:239], v245, v53, v[236:239]
	s_nop 0
	v_mfma_f32_4x4x1_16b_f32 v[232:235], v248, v56, v[232:235]
	v_mfma_f32_4x4x1_16b_f32 v[236:239], v248, v57, v[236:239]
	s_nop 0
	v_mfma_f32_4x4x1_16b_f32 v[232:235], v249, v54, v[232:235]
	v_mfma_f32_4x4x1_16b_f32 v[236:239], v249, v55, v[236:239]
	s_nop 0
	ds_read_b128 v[20:23], v254 offset:512
	ds_read_b64 v[244:245], v254 offset:528
	ds_read_b64 v[248:249], v254 offset:536
	s_waitcnt lgkmcnt(3)
	v_mfma_f32_4x4x1_16b_f32 v[232:235], v174, v58, v[232:235]
	v_mfma_f32_4x4x1_16b_f32 v[236:239], v174, v59, v[236:239]
	s_nop 0
	v_mfma_f32_4x4x1_16b_f32 v[232:235], v175, v44, v[232:235]
	v_mfma_f32_4x4x1_16b_f32 v[236:239], v175, v45, v[236:239]
	s_nop 0
	v_mfma_f32_4x4x1_16b_f32 v[232:235], v176, v48, v[232:235]
	v_mfma_f32_4x4x1_16b_f32 v[236:239], v176, v49, v[236:239]
	s_nop 0
	v_mfma_f32_4x4x1_16b_f32 v[232:235], v177, v46, v[232:235]
	v_mfma_f32_4x4x1_16b_f32 v[236:239], v177, v47, v[236:239]
	s_nop 0
	v_mfma_f32_4x4x1_16b_f32 v[232:235], v188, v50, v[232:235]
	v_mfma_f32_4x4x1_16b_f32 v[236:239], v188, v51, v[236:239]
	s_nop 0
	v_mfma_f32_4x4x1_16b_f32 v[232:235], v189, v36, v[232:235]
	v_mfma_f32_4x4x1_16b_f32 v[236:239], v189, v37, v[236:239]
	s_nop 0
	v_mfma_f32_4x4x1_16b_f32 v[232:235], v190, v40, v[232:235]
	v_mfma_f32_4x4x1_16b_f32 v[236:239], v190, v41, v[236:239]
	s_nop 0
	v_mfma_f32_4x4x1_16b_f32 v[232:235], v191, v38, v[232:235]
	v_mfma_f32_4x4x1_16b_f32 v[236:239], v191, v39, v[236:239]
	s_nop 0
	ds_read_b128 v[174:177], v254 offset:544
	ds_read_b128 v[188:191], v254 offset:560
	s_nop 4
	v_fma_f32 v146, v42, v144, v232
	v_fma_f32 v147, v43, v145, v236
	v_fma_f32 v146, v70, v145, v146
	v_fma_f32 v147, v71, v144, v147
	v_fma_f32 v160, v42, v146, v233
	v_fma_f32 v161, v43, v147, v237
	v_fma_f32 v160, v70, v147, v160
	v_fma_f32 v161, v71, v146, v161
	v_fma_f32 v162, v42, v160, v234
	v_fma_f32 v163, v43, v161, v238
	v_fma_f32 v162, v70, v161, v162
	v_fma_f32 v163, v71, v160, v163
	v_fma_f32 v164, v42, v162, v235
	v_fma_f32 v165, v43, v163, v239
	v_fma_f32 v164, v70, v163, v164
	v_fma_f32 v165, v71, v162, v165
	s_waitcnt lgkmcnt(2)
; #define LAS __attribute__((address_space(3)))
; template <bool SAMPLE>
; __device__ __forceinline__ void ssm_item(kp_t kp, LAS unsigned char* lds, int l, int item, const bf16_t* Z, float* YM, int tid, int lane, int wave) {
;     ...
;         for (int tt = 0; tt < 16; ++tt) { const LAS f32x4* up = (const LAS f32x4*)(U + (wave * 16 + tt) * 16);
;             if (SAMPLE && (tt & 3) == 0) h = h0[tt >> 2];
;             f32x2 bu = (f32x2){0.f, 0.f};
; #pragma unroll
;             for (int q = 0; q < 4; ++q) { const f32x4 u = up[q];
; #pragma unroll
;                 for (int e = 0; e < 4; ++e) bu = __builtin_elementwise_fma(B2[4 * q + e], (f32x2){u[e], u[e]}, bu); }
;             const f32x2 t1 = __builtin_elementwise_fma((f32x2){lr, lr}, h, bu);
;             h = __builtin_elementwise_fma((f32x2){-li, li}, (f32x2){h.y, h.x}, t1); hl[tt] = h;
;             if (SAMPLE && (tt & 3) == 3) { const size_t si = ((size_t)(l * 128 + b * 32 + wave * 4 + (tt >> 2)) * 64 + g) * 64 + p; OUTP[O_SRE + si] = h.x; OUTP[O_SIM + si] = h.y; } }
;         float cr_ = car, ci_ = cai, cwr = 0.f, cwi = 0.f;
;         if (!SAMPLE) {
;         Eb[wave * 64 + p] = h;
;         __syncthreads();
	v_mfma_f32_4x4x1_16b_f32 v[232:235], v20, v72, 0
	v_mfma_f32_4x4x1_16b_f32 v[236:239], v20, v73, 0
	s_nop 0
	v_mfma_f32_4x4x1_16b_f32 v[232:235], v21, v64, v[232:235]
	v_mfma_f32_4x4x1_16b_f32 v[236:239], v21, v65, v[236:239]
	s_nop 0
	v_mfma_f32_4x4x1_16b_f32 v[232:235], v22, v60, v[232:235]
	v_mfma_f32_4x4x1_16b_f32 v[236:239], v22, v61, v[236:239]
	s_nop 0
	v_mfma_f32_4x4x1_16b_f32 v[232:235], v23, v62, v[232:235]
	v_mfma_f32_4x4x1_16b_f32 v[236:239], v23, v63, v[236:239]
	s_nop 0
	v_mfma_f32_4x4x1_16b_f32 v[232:235], v244, v66, v[232:235]
	v_mfma_f32_4x4x1_16b_f32 v[236:239], v244, v67, v[236:239]
	s_nop 0
	v_mfma_f32_4x4x1_16b_f32 v[232:235], v245, v52, v[232:235]
	v_mfma_f32_4x4x1_16b_f32 v[236:239], v245, v53, v[236:239]
	s_nop 0
	v_mfma_f32_4x4x1_16b_f32 v[232:235], v248, v56, v[232:235]
	v_mfma_f32_4x4x1_16b_f32 v[236:239], v248, v57, v[236:239]
	s_nop 0
	v_mfma_f32_4x4x1_16b_f32 v[232:235], v249, v54, v[232:235]
	v_mfma_f32_4x4x1_16b_f32 v[236:239], v249, v55, v[236:239]
	s_nop 0
	ds_read_b128 v[20:23], v254 offset:768
	ds_read_b64 v[244:245], v254 offset:784
	ds_read_b64 v[248:249], v254 offset:792
	s_waitcnt lgkmcnt(3)
	v_mfma_f32_4x4x1_16b_f32 v[232:235], v174, v58, v[232:235]
	v_mfma_f32_4x4x1_16b_f32 v[236:239], v174, v59, v[236:239]
	s_nop 0
	v_mfma_f32_4x4x1_16b_f32 v[232:235], v175, v44, v[232:235]
	v_mfma_f32_4x4x1_16b_f32 v[236:239], v175, v45, v[236:239]
	s_nop 0
	v_mfma_f32_4x4x1_16b_f32 v[232:235], v176, v48, v[232:235]
	v_mfma_f32_4x4x1_16b_f32 v[236:239], v176, v49, v[236:239]
	s_nop 0
	v_mfma_f32_4x4x1_16b_f32 v[232:235], v177, v46, v[232:235]
	v_mfma_f32_4x4x1_16b_f32 v[236:239], v177, v47, v[236:239]
	s_nop 0
	v_mfma_f32_4x4x1_16b_f32 v[232:235], v188, v50, v[232:235]
	v_mfma_f32_4x4x1_16b_f32 v[236:239], v188, v51, v[236:239]
	s_nop 0
	v_mfma_f32_4x4x1_16b_f32 v[232:235], v189, v36, v[232:235]
	v_mfma_f32_4x4x1_16b_f32 v[236:239], v189, v37, v[236:239]
	s_nop 0
	v_mfma_f32_4x4x1_16b_f32 v[232:235], v190, v40, v[232:235]
	v_mfma_f32_4x4x1_16b_f32 v[236:239], v190, v41, v[236:239]
	s_nop 0
	v_mfma_f32_4x4x1_16b_f32 v[232:235], v191, v38, v[232:235]
	v_mfma_f32_4x4x1_16b_f32 v[236:239], v191, v39, v[236:239]
	s_nop 0
	ds_read_b128 v[174:177], v254 offset:800
	ds_read_b128 v[188:191], v254 offset:816
	s_nop 4
	v_fma_f32 v166, v42, v164, v232
	v_fma_f32 v167, v43, v165, v236
	v_fma_f32 v166, v70, v165, v166
	v_fma_f32 v167, v71, v164, v167
	v_fma_f32 v168, v42, v166, v233
	v_fma_f32 v169, v43, v167, v237
	v_fma_f32 v168, v70, v167, v168
	v_fma_f32 v169, v71, v166, v169
	v_fma_f32 v170, v42, v168, v234
	v_fma_f32 v171, v43, v169, v238
	v_fma_f32 v170, v70, v169, v170
	v_fma_f32 v171, v71, v168, v171
	v_fma_f32 v172, v42, v170, v235
	v_fma_f32 v173, v43, v171, v239
	v_fma_f32 v172, v70, v171, v172
	v_fma_f32 v173, v71, v170, v173
	s_waitcnt lgkmcnt(2)
	v_mfma_f32_4x4x1_16b_f32 v[232:235], v20, v72, 0
	v_mfma_f32_4x4x1_16b_f32 v[236:239], v20, v73, 0
	s_nop 0
	v_mfma_f32_4x4x1_16b_f32 v[232:235], v21, v64, v[232:235]
	v_mfma_f32_4x4x1_16b_f32 v[236:239], v21, v65, v[236:239]
	s_nop 0
	v_mfma_f32_4x4x1_16b_f32 v[232:235], v22, v60, v[232:235]
	v_mfma_f32_4x4x1_16b_f32 v[236:239], v22, v61, v[236:239]
	s_nop 0
	v_mfma_f32_4x4x1_16b_f32 v[232:235], v23, v62, v[232:235]
	v_mfma_f32_4x4x1_16b_f32 v[236:239], v23, v63, v[236:239]
	s_nop 0
	v_mfma_f32_4x4x1_16b_f32 v[232:235], v244, v66, v[232:235]
	v_mfma_f32_4x4x1_16b_f32 v[236:239], v244, v67, v[236:239]
	s_nop 0
	v_mfma_f32_4x4x1_16b_f32 v[232:235], v245, v52, v[232:235]
	v_mfma_f32_4x4x1_16b_f32 v[236:239], v245, v53, v[236:239]
	s_nop 0
	v_mfma_f32_4x4x1_16b_f32 v[232:235], v248, v56, v[232:235]
	v_mfma_f32_4x4x1_16b_f32 v[236:239], v248, v57, v[236:239]
	s_nop 0
	v_mfma_f32_4x4x1_16b_f32 v[232:235], v249, v54, v[232:235]
	v_mfma_f32_4x4x1_16b_f32 v[236:239], v249, v55, v[236:239]
	s_nop 0
	s_waitcnt lgkmcnt(0)
	v_mfma_f32_4x4x1_16b_f32 v[232:235], v174, v58, v[232:235]
	v_mfma_f32_4x4x1_16b_f32 v[236:239], v174, v59, v[236:239]
	s_nop 0
	v_mfma_f32_4x4x1_16b_f32 v[232:235], v175, v44, v[232:235]
	v_mfma_f32_4x4x1_16b_f32 v[236:239], v175, v45, v[236:239]
	s_nop 0
	v_mfma_f32_4x4x1_16b_f32 v[232:235], v176, v48, v[232:235]
	v_mfma_f32_4x4x1_16b_f32 v[236:239], v176, v49, v[236:239]
	s_nop 0
	v_mfma_f32_4x4x1_16b_f32 v[232:235], v177, v46, v[232:235]
	v_mfma_f32_4x4x1_16b_f32 v[236:239], v177, v47, v[236:239]
	s_nop 0
	v_mfma_f32_4x4x1_16b_f32 v[232:235], v188, v50, v[232:235]
	v_mfma_f32_4x4x1_16b_f32 v[236:239], v188, v51, v[236:239]
	s_nop 0
	v_mfma_f32_4x4x1_16b_f32 v[232:235], v189, v36, v[232:235]
	v_mfma_f32_4x4x1_16b_f32 v[236:239], v189, v37, v[236:239]
	s_nop 0
	v_mfma_f32_4x4x1_16b_f32 v[232:235], v190, v40, v[232:235]
	v_mfma_f32_4x4x1_16b_f32 v[236:239], v190, v41, v[236:239]
	s_nop 0
	v_mfma_f32_4x4x1_16b_f32 v[232:235], v191, v38, v[232:235]
	v_mfma_f32_4x4x1_16b_f32 v[236:239], v191, v39, v[236:239]
	s_nop 0
	s_nop 4
	v_fma_f32 v174, v42, v172, v232
	v_fma_f32 v175, v43, v173, v236
	v_fma_f32 v174, v70, v173, v174
	v_fma_f32 v175, v71, v172, v175
	v_fma_f32 v176, v42, v174, v233
	v_fma_f32 v177, v43, v175, v237
	v_fma_f32 v176, v70, v175, v176
	v_fma_f32 v177, v71, v174, v177
	v_fma_f32 v188, v42, v176, v234
	v_fma_f32 v189, v43, v177, v238
	v_fma_f32 v188, v70, v177, v188
	v_fma_f32 v189, v71, v176, v189
	v_fma_f32 v190, v42, v188, v235
	v_fma_f32 v191, v43, v189, v239
	v_fma_f32 v190, v70, v189, v190
	v_fma_f32 v191, v71, v188, v191
	v_cndmask_b32_e64 v22, 0, v132, s[0:1]
	ds_write_b64 v217, v[190:191] offset:16384
	s_waitcnt lgkmcnt(0)
	s_barrier
; #define LAS __attribute__((address_space(3)))
; __device__ __forceinline__ unsigned cvt_pk_bf16(float lo, float hi) { unsigned r; asm("v_cvt_pk_bf16_f32 %0, %1, %2" : "=v"(r) : "v"(lo), "v"(hi)); return r; }
; template <bool SAMPLE>
; __device__ __forceinline__ void ssm_item(kp_t kp, LAS unsigned char* lds, int l, int item, const bf16_t* Z, float* YM, int tid, int lane, int wave) {
;     ...
;         for (int v = 0; v < 8; ++v) { if (v == wave) { cwr = cr_; cwi = ci_; } const f32x2 e = Eb[v * 64 + p];
;             const float nr = l16r * cr_ - l16i * ci_ + e.x, ni = l16r * ci_ + l16i * cr_ + e.y; cr_ = nr; ci_ = ni; }
;         car = cr_; cai = ci_;
;         }
; #pragma unroll
;         for (int tt = 0; tt < 16; ++tt) {
;             const f32x2 t1 = __builtin_elementwise_fma(pw[tt], (f32x2){cwr, cwr}, hl[tt]);
;             const f32x2 h2 = __builtin_elementwise_fma((f32x2){-pw[tt].y, pw[tt].x}, (f32x2){cwi, cwi}, t1);
;             *(LAS unsigned*)(Hb + (wave * 16 + tt) * 272 + p * 4) = cvt_pk_bf16(h2.x, h2.y); }
	ds_read2st64_b64 v[232:235], v218 offset0:32 offset1:33
	ds_read2st64_b64 v[236:239], v218 offset0:34 offset1:35
	v_mul_f32_e32 v20, v109, v133
	v_pk_fma_f32 v[20:21], v[108:109], v[132:133], v[20:21] op_sel_hi:[1,1,0] neg_lo:[0,0,1] neg_hi:[0,0,1]
	v_pk_fma_f32 v[132:133], v[106:107], v[132:133], v[246:247] op_sel_hi:[1,1,0]
	s_waitcnt lgkmcnt(1)
	v_pk_add_f32 v[244:245], v[20:21], v[232:233]
	v_pk_add_f32 v[132:133], v[132:133], v[232:233] op_sel:[0,1] op_sel_hi:[1,0]
	v_cndmask_b32_e64 v248, v22, v244, s[16:17]
	v_cndmask_b32_e64 v246, v247, v132, s[16:17]
	v_pk_mul_f32 v[132:133], v[106:107], v[132:133] op_sel_hi:[1,0]
	ds_read2st64_b64 v[240:243], v218 offset0:36 offset1:37
	ds_read2st64_b64 v[20:23], v218 offset0:38 offset1:39
	v_pk_fma_f32 v[232:233], v[108:109], v[244:245], v[132:133] neg_lo:[0,0,1] neg_hi:[0,0,1]
	v_pk_fma_f32 v[132:133], v[108:109], v[244:245], v[132:133] op_sel_hi:[1,0,1]
	s_nop 0
	v_mov_b32_e32 v233, v133
	v_pk_add_f32 v[132:133], v[234:235], v[232:233]
	s_nop 0
	v_cndmask_b32_e64 v235, v248, v132, s[4:5]
	v_mul_f32_e32 v232, v109, v133
	v_mul_f32_e32 v234, v106, v132
	v_cndmask_b32_e64 v244, v246, v133, s[4:5]
	v_pk_fma_f32 v[232:233], v[108:109], v[132:133], v[232:233] op_sel_hi:[1,1,0] neg_lo:[0,0,1] neg_hi:[0,0,1]
	v_pk_fma_f32 v[132:133], v[106:107], v[132:133], v[234:235] op_sel_hi:[1,1,0]
	s_nop 0
	v_mov_b32_e32 v233, v133
	s_waitcnt lgkmcnt(2)
	v_pk_add_f32 v[132:133], v[236:237], v[232:233]
	s_nop 0
	v_pk_mul_f32 v[232:233], v[102:103], v[132:133]
	v_cndmask_b32_e64 v236, v235, v132, s[6:7]
	v_cndmask_b32_e64 v237, v244, v133, s[6:7]
	v_pk_fma_f32 v[234:235], v[104:105], v[132:133], v[232:233] op_sel:[0,0,1] op_sel_hi:[1,1,0] neg_lo:[0,0,1] neg_hi:[0,0,1]
	v_pk_fma_f32 v[132:133], v[104:105], v[132:133], v[232:233] op_sel:[0,0,1] op_sel_hi:[1,1,0]
	s_nop 0
	v_mov_b32_e32 v235, v133
	v_pk_add_f32 v[132:133], v[238:239], v[234:235]
	s_nop 0
	v_pk_mul_f32 v[232:233], v[102:103], v[132:133]
	v_cndmask_b32_e64 v236, v236, v132, s[8:9]
	v_cndmask_b32_e64 v237, v237, v133, s[8:9]
	v_pk_fma_f32 v[234:235], v[104:105], v[132:133], v[232:233] op_sel:[0,0,1] op_sel_hi:[1,1,0] neg_lo:[0,0,1] neg_hi:[0,0,1]
	v_pk_fma_f32 v[132:133], v[104:105], v[132:133], v[232:233] op_sel:[0,0,1] op_sel_hi:[1,1,0]
	s_nop 0
	v_mov_b32_e32 v235, v133
	s_waitcnt lgkmcnt(1)
	v_pk_add_f32 v[132:133], v[240:241], v[234:235]
	s_nop 0
	v_pk_mul_f32 v[232:233], v[102:103], v[132:133]
	v_cndmask_b32_e64 v236, v236, v132, s[10:11]
	v_cndmask_b32_e64 v237, v237, v133, s[10:11]
	v_pk_fma_f32 v[234:235], v[104:105], v[132:133], v[232:233] op_sel:[0,0,1] op_sel_hi:[1,1,0] neg_lo:[0,0,1] neg_hi:[0,0,1]
	v_pk_fma_f32 v[132:133], v[104:105], v[132:133], v[232:233] op_sel:[0,0,1] op_sel_hi:[1,1,0]
	s_nop 0
	v_mov_b32_e32 v235, v133
	v_pk_add_f32 v[232:233], v[242:243], v[234:235]
	s_nop 0
	v_mul_f32_e32 v132, v109, v233
	v_cndmask_b32_e64 v235, v236, v232, s[12:13]
	v_pk_fma_f32 v[132:133], v[108:109], v[232:233], v[132:133] op_sel_hi:[1,1,0] neg_lo:[0,0,1] neg_hi:[0,0,1]
	v_mul_f32_e32 v234, v107, v233
	v_cndmask_b32_e64 v236, v237, v233, s[12:13]
	s_waitcnt lgkmcnt(0)
	v_pk_add_f32 v[132:133], v[20:21], v[132:133]
	v_pk_fma_f32 v[232:233], v[106:107], v[232:233], v[234:235] op_sel_hi:[1,1,0]
	s_nop 0
	v_pk_add_f32 v[20:21], v[20:21], v[232:233] op_sel:[1,0] op_sel_hi:[0,1]
	v_cndmask_b32_e64 v232, v235, v132, s[14:15]
	v_cndmask_b32_e64 v234, v236, v20, s[14:15]
	v_pk_fma_f32 v[138:139], v[68:69], v[232:233], v[138:139] op_sel_hi:[1,0,1]
	v_pk_mul_f32 v[20:21], v[106:107], v[20:21] op_sel_hi:[1,0]
	v_pk_fma_f32 v[138:139], v[26:27], v[234:235], v[138:139] op_sel_hi:[1,0,1]
	s_nop 0
	v_cvt_pk_bf16_f32 v233, v138, v139
	s_nop 0
	v_pk_fma_f32 v[138:139], v[74:75], v[232:233], v[140:141] op_sel_hi:[1,0,1]
	v_add_u32_e32 v140, 0x5000, v148
	v_pk_fma_f32 v[138:139], v[28:29], v[234:235], v[138:139] op_sel_hi:[1,0,1]
	s_nop 0
	v_cvt_pk_bf16_f32 v138, v138, v139
	ds_write2_b32 v140, v233, v138 offset1:68
	v_pk_fma_f32 v[138:139], v[76:77], v[232:233], v[142:143] op_sel_hi:[1,0,1]
	s_nop 0
	v_pk_fma_f32 v[138:139], v[30:31], v[234:235], v[138:139] op_sel_hi:[1,0,1]
	s_nop 0
	v_cvt_pk_bf16_f32 v141, v138, v139
	v_pk_fma_f32 v[138:139], v[78:79], v[232:233], v[144:145] op_sel_hi:[1,0,1]
	s_nop 0
	v_pk_fma_f32 v[138:139], v[32:33], v[234:235], v[138:139] op_sel_hi:[1,0,1]
	s_nop 0
	v_cvt_pk_bf16_f32 v138, v138, v139
	ds_write2_b32 v140, v141, v138 offset0:136 offset1:204
	v_pk_fma_f32 v[138:139], v[80:81], v[232:233], v[146:147] op_sel_hi:[1,0,1]
	v_add_u32_e32 v141, 0x5400, v148
	v_pk_fma_f32 v[138:139], v[34:35], v[234:235], v[138:139] op_sel_hi:[1,0,1]
	v_lshl_add_u32 v146, v219, 2, s3
	v_cvt_pk_bf16_f32 v140, v138, v139
	v_pk_fma_f32 v[138:139], v[82:83], v[232:233], v[160:161] op_sel_hi:[1,0,1]
	s_nop 0
	v_pk_fma_f32 v[138:139], v[110:111], v[234:235], v[138:139] op_sel_hi:[1,0,1]
	s_nop 0
	v_cvt_pk_bf16_f32 v138, v138, v139
	ds_write2_b32 v141, v140, v138 offset0:16 offset1:84
	v_pk_fma_f32 v[138:139], v[84:85], v[232:233], v[162:163] op_sel_hi:[1,0,1]
	s_nop 0
	v_pk_fma_f32 v[138:139], v[112:113], v[234:235], v[138:139] op_sel_hi:[1,0,1]
	s_nop 0
	v_cvt_pk_bf16_f32 v140, v138, v139
	v_pk_fma_f32 v[138:139], v[86:87], v[232:233], v[164:165] op_sel_hi:[1,0,1]
	s_nop 0
	v_pk_fma_f32 v[138:139], v[114:115], v[234:235], v[138:139] op_sel_hi:[1,0,1]
	s_nop 0
	v_cvt_pk_bf16_f32 v138, v138, v139
	ds_write2_b32 v141, v140, v138 offset0:152 offset1:220
	v_pk_fma_f32 v[138:139], v[88:89], v[232:233], v[166:167] op_sel_hi:[1,0,1]
	v_add_u32_e32 v141, 0x5800, v148
	v_pk_fma_f32 v[138:139], v[116:117], v[234:235], v[138:139] op_sel_hi:[1,0,1]
	s_nop 0
; #define LAS __attribute__((address_space(3)))
; __device__ __forceinline__ unsigned cvt_pk_bf16(float lo, float hi) { unsigned r; asm("v_cvt_pk_bf16_f32 %0, %1, %2" : "=v"(r) : "v"(lo), "v"(hi)); return r; }
; #define LDS_WAIT() asm volatile("s_waitcnt lgkmcnt(0)" ::: "memory")
; template <bool SAMPLE>
; __device__ __forceinline__ void ssm_item(kp_t kp, LAS unsigned char* lds, int l, int item, const bf16_t* Z, float* YM, int tid, int lane, int wave) {
;     ...
;         for (int tt = 0; tt < 16; ++tt) {
;             const f32x2 t1 = __builtin_elementwise_fma(pw[tt], (f32x2){cwr, cwr}, hl[tt]);
;             const f32x2 h2 = __builtin_elementwise_fma((f32x2){-pw[tt].y, pw[tt].x}, (f32x2){cwi, cwi}, t1);
;             *(LAS unsigned*)(Hb + (wave * 16 + tt) * 272 + p * 4) = cvt_pk_bf16(h2.x, h2.y); }
;         LDS_WAIT();
;         f32x4 acc = (f32x4){0.f, 0.f, 0.f, 0.f};
; #pragma unroll
;         for (int ks = 0; ks < 4; ++ks) { const bf16x8 av = *(const LAS bf16x8*)(Hb + (wave * 16 + fr) * 272 + (ks * 32 + fq * 8) * 2);
;             acc = __builtin_amdgcn_mfma_f32_16x16x32_bf16(av, cf[ks], acc, 0, 0, 0); }
;         float yv[4];
; #pragma unroll
;         for (int j = 0; j < 4; ++j) { const int t = wave * 16 + fq * 4 + j; float y = acc[j] + Dv * U[t * 16 + fr]; y = gelu_tanh(y); yv[j] = y; Yb[t * 16 + fr] = y; }
	v_cvt_pk_bf16_f32 v140, v138, v139
	v_pk_fma_f32 v[138:139], v[90:91], v[232:233], v[168:169] op_sel_hi:[1,0,1]
	s_nop 0
	v_pk_fma_f32 v[138:139], v[118:119], v[234:235], v[138:139] op_sel_hi:[1,0,1]
	s_nop 0
	v_cvt_pk_bf16_f32 v138, v138, v139
	ds_write2_b32 v141, v140, v138 offset0:32 offset1:100
	v_pk_fma_f32 v[138:139], v[92:93], v[232:233], v[170:171] op_sel_hi:[1,0,1]
	s_nop 0
	v_pk_fma_f32 v[138:139], v[120:121], v[234:235], v[138:139] op_sel_hi:[1,0,1]
	s_nop 0
	v_cvt_pk_bf16_f32 v140, v138, v139
	v_pk_fma_f32 v[138:139], v[94:95], v[232:233], v[172:173] op_sel_hi:[1,0,1]
	s_nop 0
	v_pk_fma_f32 v[138:139], v[122:123], v[234:235], v[138:139] op_sel_hi:[1,0,1]
	s_nop 0
	v_cvt_pk_bf16_f32 v138, v138, v139
	ds_write2_b32 v141, v140, v138 offset0:168 offset1:236
	v_pk_fma_f32 v[138:139], v[96:97], v[232:233], v[174:175] op_sel_hi:[1,0,1]
	v_add_u32_e32 v141, 0x5c00, v148
	v_pk_fma_f32 v[138:139], v[124:125], v[234:235], v[138:139] op_sel_hi:[1,0,1]
	s_nop 0
	v_cvt_pk_bf16_f32 v140, v138, v139
	v_pk_fma_f32 v[138:139], v[98:99], v[232:233], v[176:177] op_sel_hi:[1,0,1]
	s_nop 0
	v_pk_fma_f32 v[138:139], v[126:127], v[234:235], v[138:139] op_sel_hi:[1,0,1]
	s_nop 0
	v_cvt_pk_bf16_f32 v138, v138, v139
	ds_write2_b32 v141, v140, v138 offset0:48 offset1:116
	v_pk_fma_f32 v[138:139], v[100:101], v[232:233], v[188:189] op_sel_hi:[1,0,1]
	s_nop 0
	v_pk_fma_f32 v[138:139], v[128:129], v[234:235], v[138:139] op_sel_hi:[1,0,1]
	s_nop 0
	v_cvt_pk_bf16_f32 v140, v138, v139
	v_pk_fma_f32 v[138:139], v[108:109], v[232:233], v[190:191] op_sel_hi:[1,0,1]
	s_nop 0
	v_pk_fma_f32 v[138:139], v[130:131], v[234:235], v[138:139] op_sel_hi:[1,0,1]
	s_nop 0
	v_cvt_pk_bf16_f32 v138, v138, v139
	ds_write2_b32 v141, v140, v138 offset0:184 offset1:252
	s_waitcnt lgkmcnt(0)
	ds_read_b128 v[138:141], v227 offset:20480
	ds_read_b128 v[142:145], v227 offset:20544
	s_waitcnt lgkmcnt(1)
	v_mfma_f32_16x16x32_bf16 v[138:141], v[138:141], v[4:7], 0
	ds_read_b128 v[160:163], v227 offset:20608
	ds_read_b32 v146, v146
	s_waitcnt lgkmcnt(2)
	v_mfma_f32_16x16x32_bf16 v[138:141], v[142:145], v[8:11], v[138:141]
	ds_read_b128 v[142:145], v227 offset:20672
	s_waitcnt lgkmcnt(2)
	v_mfma_f32_16x16x32_bf16 v[138:141], v[160:163], v[12:15], v[138:141]
	s_waitcnt lgkmcnt(0)
	v_mfma_f32_16x16x32_bf16 v[138:141], v[142:145], v[16:19], v[138:141]
	s_nop 7
	v_fma_f32 v138, v200, v146, v138
	v_mul_f32_e32 v142, 0x3d372713, v138
	v_mul_f32_e32 v142, v138, v142
	v_fma_f32 v142, v138, v142, v138
	v_mul_f32_e32 v142, 0x3f4c422a, v142
	v_add_f32_e32 v142, v142, v142
	v_mul_f32_e32 v142, 0x3fb8aa3b, v142
	v_exp_f32_e32 v142, v142
	v_mul_f32_e32 v138, 0.5, v138
	v_add_f32_e32 v142, 1.0, v142
	v_div_scale_f32 v143, s[26:27], v142, v142, 2.0
	v_rcp_f32_e32 v144, v143
	s_nop 0
	v_fma_f32 v145, -v143, v144, 1.0
	v_fmac_f32_e32 v144, v145, v144
	v_div_scale_f32 v145, vcc, 2.0, v142, 2.0
	v_mul_f32_e32 v146, v145, v144
	v_fma_f32 v147, -v143, v146, v145
	v_fmac_f32_e32 v146, v147, v144
	v_fma_f32 v143, -v143, v146, v145
	v_div_fmas_f32 v143, v143, v144, v146
	v_div_fixup_f32 v142, v143, v142, 2.0
	v_sub_f32_e32 v142, 1.0, v142
	v_add_f32_e32 v142, 1.0, v142
	v_mul_f32_e32 v168, v138, v142
	ds_write_b32 v220, v168 offset:55296
	v_lshl_add_u32 v138, v221, 2, s3
	ds_read_b32 v138, v138
	s_waitcnt lgkmcnt(0)
	v_fma_f32 v138, v200, v138, v139
	v_mul_f32_e32 v139, 0x3d372713, v138
	v_mul_f32_e32 v139, v138, v139
	v_fma_f32 v139, v138, v139, v138
	v_mul_f32_e32 v139, 0x3f4c422a, v139
	v_add_f32_e32 v139, v139, v139
	v_mul_f32_e32 v139, 0x3fb8aa3b, v139
	v_exp_f32_e32 v139, v139
	v_mul_f32_e32 v138, 0.5, v138
	v_add_f32_e32 v139, 1.0, v139
	v_div_scale_f32 v142, s[26:27], v139, v139, 2.0
	v_rcp_f32_e32 v143, v142
	s_nop 0
	v_fma_f32 v144, -v142, v143, 1.0
	v_fmac_f32_e32 v143, v144, v143
	v_div_scale_f32 v144, vcc, 2.0, v139, 2.0
	v_mul_f32_e32 v145, v144, v143
	v_fma_f32 v146, -v142, v145, v144
	v_fmac_f32_e32 v145, v146, v143
	v_fma_f32 v142, -v142, v145, v144
	v_div_fmas_f32 v142, v142, v143, v145
	v_div_fixup_f32 v139, v142, v139, 2.0
	v_sub_f32_e32 v139, 1.0, v139
	v_add_f32_e32 v139, 1.0, v139
	v_mul_f32_e32 v169, v138, v139
	ds_write_b32 v222, v169 offset:55296
	v_lshl_add_u32 v138, v223, 2, s3
	ds_read_b32 v138, v138
	v_pk_fma_f32 v[146:147], v[108:109], v[132:133], v[20:21] neg_lo:[0,0,1] neg_hi:[0,0,1]
	v_pk_fma_f32 v[20:21], v[108:109], v[132:133], v[20:21] op_sel_hi:[1,0,1]
	s_waitcnt lgkmcnt(0)
	v_fma_f32 v138, v200, v138, v140
	v_mul_f32_e32 v139, 0x3d372713, v138
	v_mul_f32_e32 v139, v138, v139
	v_fma_f32 v139, v138, v139, v138
	v_mul_f32_e32 v139, 0x3f4c422a, v139
	v_add_f32_e32 v139, v139, v139
	v_mul_f32_e32 v139, 0x3fb8aa3b, v139
	v_exp_f32_e32 v139, v139
	v_mul_f32_e32 v138, 0.5, v138
	v_mov_b32_e32 v147, v21
	v_add_f32_e32 v139, 1.0, v139
	v_div_scale_f32 v140, s[26:27], v139, v139, 2.0
	v_rcp_f32_e32 v142, v140
	s_nop 0
	v_fma_f32 v143, -v140, v142, 1.0
	v_fmac_f32_e32 v142, v143, v142
	v_div_scale_f32 v143, vcc, 2.0, v139, 2.0
	v_mul_f32_e32 v144, v143, v142
	v_fma_f32 v145, -v140, v144, v143
	v_fmac_f32_e32 v144, v145, v142
	v_fma_f32 v140, -v140, v144, v143
	v_div_fmas_f32 v140, v140, v142, v144
	v_div_fixup_f32 v139, v140, v139, 2.0
	v_sub_f32_e32 v139, 1.0, v139
	v_add_f32_e32 v139, 1.0, v139
	v_mul_f32_e32 v170, v138, v139
	ds_write_b32 v224, v170 offset:55296
	v_lshl_add_u32 v138, v225, 2, s3
	ds_read_b32 v138, v138
	s_mov_b32 s3, 0x10d00000
	s_waitcnt lgkmcnt(0)
; #define LAS __attribute__((address_space(3)))
; #define LDS_WAIT() asm volatile("s_waitcnt lgkmcnt(0)" ::: "memory")
; __device__ __forceinline__ float sigmoidf(float s) { return 1.0f / (1.0f + __expf(-s)); }
; template <bool SAMPLE>
; __device__ __forceinline__ void ssm_item(kp_t kp, LAS unsigned char* lds, int l, int item, const bf16_t* Z, float* YM, int tid, int lane, int wave) {
;     ...
;         for (int j = 0; j < 4; ++j) { const int t = wave * 16 + fq * 4 + j; float y = acc[j] + Dv * U[t * 16 + fr]; y = gelu_tanh(y); yv[j] = y; Yb[t * 16 + fr] = y; }
;         LDS_WAIT();
; #pragma unroll
;         for (int j = 0; j < 4; ++j) { const int t = wave * 16 + fq * 4 + j; const LAS f32x4* yp = (const LAS f32x4*)(Yb + t * 16); float s = 0.f;
; #pragma unroll
;             for (int q = 0; q < 4; ++q) { const f32x4 v = yp[q]; s += (v[0] * wg[4 * q] + v[1] * wg[4 * q + 1]) + (v[2] * wg[4 * q + 2] + v[3] * wg[4 * q + 3]); }
;             YM[(tok0 + t) * DM + g * 16 + fr] = yv[j] * sigmoidf(s); }
	v_fmac_f32_e32 v141, v200, v138
	v_mul_f32_e32 v138, 0x3d372713, v141
	v_mul_f32_e32 v138, v141, v138
	v_fma_f32 v138, v141, v138, v141
	v_mul_f32_e32 v138, 0x3f4c422a, v138
	v_add_f32_e32 v138, v138, v138
	v_mul_f32_e32 v138, 0x3fb8aa3b, v138
	v_exp_f32_e32 v138, v138
	s_nop 0
	v_add_f32_e32 v138, 1.0, v138
	v_div_scale_f32 v139, s[26:27], v138, v138, 2.0
	v_rcp_f32_e32 v140, v139
	s_nop 0
	v_fma_f32 v142, -v139, v140, 1.0
	v_fmac_f32_e32 v140, v142, v140
	v_div_scale_f32 v142, vcc, 2.0, v138, 2.0
	v_mul_f32_e32 v143, v142, v140
	v_fma_f32 v144, -v139, v143, v142
	v_fmac_f32_e32 v143, v144, v140
	v_fma_f32 v139, -v139, v143, v142
	v_div_fmas_f32 v139, v139, v140, v143
	v_div_fixup_f32 v138, v139, v138, 2.0
	v_sub_f32_e32 v138, 1.0, v138
	v_mul_f32_e32 v139, 0.5, v141
	v_add_f32_e32 v138, 1.0, v138
	v_mul_f32_e32 v171, v139, v138
	ds_write_b32 v226, v171 offset:55296
	s_waitcnt lgkmcnt(0)
	ds_read_b128 v[138:141], v228 offset:55296
	ds_read_b128 v[142:145], v228 offset:55312
	ds_read_b128 v[160:163], v228 offset:55328
	ds_read_b128 v[164:167], v228 offset:55344
	s_waitcnt lgkmcnt(3)
	v_mul_f32_e32 v139, v202, v139
	v_fmac_f32_e32 v139, v201, v138
	v_mul_f32_e32 v138, v204, v141
	v_fmac_f32_e32 v138, v203, v140
	v_add_f32_e32 v138, v139, v138
	s_waitcnt lgkmcnt(2)
	v_mul_f32_e32 v139, v206, v143
	v_mul_f32_e32 v140, v208, v145
	v_fmac_f32_e32 v139, v205, v142
	v_fmac_f32_e32 v140, v207, v144
	v_add_f32_e32 v138, 0, v138
	v_add_f32_e32 v139, v139, v140
	v_add_f32_e32 v138, v138, v139
	s_waitcnt lgkmcnt(1)
	v_mul_f32_e32 v139, v210, v161
	v_mul_f32_e32 v140, v212, v163
	v_fmac_f32_e32 v139, v209, v160
	v_fmac_f32_e32 v140, v211, v162
	v_add_f32_e32 v139, v139, v140
	v_add_f32_e32 v138, v138, v139
	s_waitcnt lgkmcnt(0)
	v_mul_f32_e32 v139, v214, v165
	v_mul_f32_e32 v140, v216, v167
	v_fmac_f32_e32 v139, v213, v164
	v_fmac_f32_e32 v140, v215, v166
	v_add_f32_e32 v139, v139, v140
	v_add_f32_e32 v138, v138, v139
	v_mul_f32_e32 v138, 0xbfb8aa3b, v138
	v_exp_f32_e32 v138, v138
	s_nop 0
	v_add_f32_e32 v172, 1.0, v138
	v_div_scale_f32 v138, s[26:27], v172, v172, 1.0
	v_rcp_f32_e32 v142, v138
	s_nop 0
	v_fma_f32 v20, -v138, v142, 1.0
	v_fmac_f32_e32 v142, v20, v142
	v_div_scale_f32 v20, vcc, 1.0, v172, 1.0
	v_mul_f32_e32 v21, v20, v142
	v_fma_f32 v132, -v138, v21, v20
	v_fmac_f32_e32 v21, v132, v142
	v_fma_f32 v20, -v138, v21, v20
	ds_read_b128 v[138:141], v229 offset:55296
	v_div_fmas_f32 v20, v20, v142, v21
	ds_read_b128 v[142:145], v229 offset:55312
	ds_read_b128 v[160:163], v229 offset:55328
	ds_read_b128 v[164:167], v229 offset:55344
	v_div_fixup_f32 v20, v20, v172, 1.0
	s_waitcnt lgkmcnt(3)
	v_mul_f32_e32 v21, v202, v139
	v_mul_f32_e32 v132, v204, v141
	v_fmac_f32_e32 v21, v201, v138
	v_fmac_f32_e32 v132, v203, v140
	v_add_f32_e32 v21, v21, v132
	s_waitcnt lgkmcnt(2)
	v_mul_f32_e32 v132, v206, v143
	v_mul_f32_e32 v133, v208, v145
	v_fmac_f32_e32 v132, v205, v142
	v_fmac_f32_e32 v133, v207, v144
	v_add_f32_e32 v21, 0, v21
	v_add_f32_e32 v132, v132, v133
	v_add_f32_e32 v21, v21, v132
	s_waitcnt lgkmcnt(1)
	v_mul_f32_e32 v132, v210, v161
	v_mul_f32_e32 v133, v212, v163
	v_fmac_f32_e32 v132, v209, v160
	v_fmac_f32_e32 v133, v211, v162
	v_add_f32_e32 v132, v132, v133
	v_add_f32_e32 v21, v21, v132
	s_waitcnt lgkmcnt(0)
	v_mul_f32_e32 v132, v214, v165
	v_mul_f32_e32 v133, v216, v167
	v_fmac_f32_e32 v132, v213, v164
	v_fmac_f32_e32 v133, v215, v166
	v_add_f32_e32 v132, v132, v133
	v_add_f32_e32 v21, v21, v132
	v_mul_f32_e32 v21, 0xbfb8aa3b, v21
	v_exp_f32_e32 v132, v21
	v_mul_f32_e32 v138, v168, v20
	v_lshl_add_u64 v[20:21], v[136:137], 0, s[20:21]
	s_add_u32 s20, s20, 0x100000
	v_add_f32_e32 v168, 1.0, v132
	v_div_scale_f32 v142, s[26:27], v168, v168, 1.0
	v_rcp_f32_e32 v172, v142
	v_add_co_u32_e32 v132, vcc, s3, v20
	s_mov_b32 s3, 0x10d02000
	s_nop 0
	v_addc_co_u32_e32 v133, vcc, 0, v21, vcc
	s_waitcnt vmcnt(0)
	v_lshlrev_b32_e32 v0, 16, v2
	v_and_b32_e32 v1, 0xffff0000, v2
	v_lshlrev_b32_e32 v2, 16, v3
	v_and_b32_e32 v3, 0xffff0000, v3
	global_store_dword v[132:133], v138, off
	v_fma_f32 v132, -v142, v172, 1.0
	v_fmac_f32_e32 v172, v132, v172
	v_div_scale_f32 v132, vcc, 1.0, v168, 1.0
	v_mul_f32_e32 v133, v132, v172
	v_fma_f32 v138, -v142, v133, v132
	v_fmac_f32_e32 v133, v138, v172
	ds_read_b128 v[138:141], v230 offset:55296
	v_fma_f32 v132, -v142, v133, v132
	ds_read_b128 v[142:145], v230 offset:55312
	ds_read_b128 v[160:163], v230 offset:55328
	ds_read_b128 v[164:167], v230 offset:55344
	v_div_fmas_f32 v132, v132, v172, v133
	v_div_fixup_f32 v132, v132, v168, 1.0
	s_waitcnt lgkmcnt(3)
; #define LAS __attribute__((address_space(3)))
; __device__ __forceinline__ f32x4 ldbf4(const bf16_t* p) { const u32x2 w = *(const u32x2*)p; return (f32x4){bf_lo(w.x), bf_hi(w.x), bf_lo(w.y), bf_hi(w.y)}; }
; __device__ __forceinline__ float sigmoidf(float s) { return 1.0f / (1.0f + __expf(-s)); }
; template <bool SAMPLE>
; __device__ __forceinline__ void ssm_item(kp_t kp, LAS unsigned char* lds, int l, int item, const bf16_t* Z, float* YM, int tid, int lane, int wave) {
;     ...
;     for (int ch = 0; ch < NCH; ++ch) {
;         const size_t tok0 = row0 + ch * 128;
;         LAS float* U = Ub + (ch & 1) * 2048;
;         *(LAS f32x4*)(U + tid * 4) = ureg;
;         if (ch < NCH - 1) ureg = ldbf4(zsrc + (size_t)(ch + 1) * 128 * INW);
;     ...
;         for (int j = 0; j < 4; ++j) { const int t = wave * 16 + fq * 4 + j; const LAS f32x4* yp = (const LAS f32x4*)(Yb + t * 16); float s = 0.f;
; #pragma unroll
;             for (int q = 0; q < 4; ++q) { const f32x4 v = yp[q]; s += (v[0] * wg[4 * q] + v[1] * wg[4 * q + 1]) + (v[2] * wg[4 * q + 2] + v[3] * wg[4 * q + 3]); }
;             YM[(tok0 + t) * DM + g * 16 + fr] = yv[j] * sigmoidf(s); }
	v_mul_f32_e32 v139, v202, v139
	v_fmac_f32_e32 v139, v201, v138
	v_mul_f32_e32 v138, v204, v141
	v_fmac_f32_e32 v138, v203, v140
	v_add_f32_e32 v138, v139, v138
	s_waitcnt lgkmcnt(2)
	v_mul_f32_e32 v139, v206, v143
	v_mul_f32_e32 v140, v208, v145
	v_fmac_f32_e32 v139, v205, v142
	v_fmac_f32_e32 v140, v207, v144
	v_add_f32_e32 v138, 0, v138
	v_add_f32_e32 v139, v139, v140
	v_add_f32_e32 v138, v138, v139
	s_waitcnt lgkmcnt(1)
	v_mul_f32_e32 v139, v210, v161
	v_mul_f32_e32 v140, v212, v163
	v_fmac_f32_e32 v139, v209, v160
	v_fmac_f32_e32 v140, v211, v162
	v_add_f32_e32 v139, v139, v140
	v_add_f32_e32 v138, v138, v139
	s_waitcnt lgkmcnt(0)
	v_mul_f32_e32 v139, v214, v165
	v_mul_f32_e32 v140, v216, v167
	v_fmac_f32_e32 v139, v213, v164
	v_fmac_f32_e32 v140, v215, v166
	v_add_f32_e32 v139, v139, v140
	v_add_f32_e32 v138, v138, v139
	v_mul_f32_e32 v138, 0xbfb8aa3b, v138
	v_exp_f32_e32 v138, v138
	v_mul_f32_e32 v139, v169, v132
	v_add_co_u32_e32 v132, vcc, s3, v20
	v_add_f32_e32 v168, 1.0, v138
	v_div_scale_f32 v142, s[26:27], v168, v168, 1.0
	v_rcp_f32_e32 v169, v142
	v_addc_co_u32_e32 v133, vcc, 0, v21, vcc
	global_store_dword v[132:133], v139, off
	v_fma_f32 v132, -v142, v169, 1.0
	v_fmac_f32_e32 v169, v132, v169
	v_div_scale_f32 v132, vcc, 1.0, v168, 1.0
	v_mul_f32_e32 v133, v132, v169
	v_fma_f32 v138, -v142, v133, v132
	v_fmac_f32_e32 v133, v138, v169
	ds_read_b128 v[138:141], v231 offset:55296
	v_fma_f32 v132, -v142, v133, v132
	ds_read_b128 v[142:145], v231 offset:55312
	ds_read_b128 v[160:163], v231 offset:55328
	ds_read_b128 v[164:167], v231 offset:55344
	v_div_fmas_f32 v132, v132, v169, v133
	v_div_fixup_f32 v132, v132, v168, 1.0
	s_waitcnt lgkmcnt(3)
	v_mul_f32_e32 v139, v202, v139
	v_fmac_f32_e32 v139, v201, v138
	v_mul_f32_e32 v138, v204, v141
	v_fmac_f32_e32 v138, v203, v140
	v_add_f32_e32 v138, v139, v138
	s_waitcnt lgkmcnt(2)
	v_mul_f32_e32 v139, v206, v143
	v_mul_f32_e32 v140, v208, v145
	v_fmac_f32_e32 v139, v205, v142
	v_fmac_f32_e32 v140, v207, v144
	v_add_f32_e32 v138, 0, v138
	v_add_f32_e32 v139, v139, v140
	v_add_f32_e32 v138, v138, v139
	s_waitcnt lgkmcnt(1)
	v_mul_f32_e32 v139, v210, v161
	v_mul_f32_e32 v140, v212, v163
	v_fmac_f32_e32 v139, v209, v160
	v_fmac_f32_e32 v140, v211, v162
	v_add_f32_e32 v139, v139, v140
	v_add_f32_e32 v138, v138, v139
	s_waitcnt lgkmcnt(0)
	v_mul_f32_e32 v139, v214, v165
	v_mul_f32_e32 v140, v216, v167
	v_fmac_f32_e32 v139, v213, v164
	v_fmac_f32_e32 v140, v215, v166
	v_add_f32_e32 v139, v139, v140
	v_add_f32_e32 v138, v138, v139
	v_mul_f32_e32 v138, 0xbfb8aa3b, v138
	v_exp_f32_e32 v138, v138
	s_mov_b32 s3, 0x10d04000
	v_mul_f32_e32 v139, v170, v132
	v_add_co_u32_e32 v132, vcc, s3, v20
	v_add_f32_e32 v138, 1.0, v138
	v_div_scale_f32 v140, s[26:27], v138, v138, 1.0
	v_rcp_f32_e32 v141, v140
	v_addc_co_u32_e32 v133, vcc, 0, v21, vcc
	global_store_dword v[132:133], v139, off
	v_fma_f32 v132, -v140, v141, 1.0
	v_fmac_f32_e32 v141, v132, v141
	v_div_scale_f32 v132, vcc, 1.0, v138, 1.0
	v_mul_f32_e32 v133, v132, v141
	v_fma_f32 v139, -v140, v133, v132
	v_fmac_f32_e32 v133, v139, v141
	v_fma_f32 v132, -v140, v133, v132
	v_div_fmas_f32 v132, v132, v141, v133
	s_mov_b32 s3, 0x10d06000
	v_div_fixup_f32 v132, v132, v138, 1.0
	v_add_co_u32_e32 v20, vcc, s3, v20
	v_mul_f32_e32 v132, v171, v132
	s_nop 0
	v_addc_co_u32_e32 v21, vcc, 0, v21, vcc
	global_store_dword v[20:21], v132, off
	s_waitcnt lgkmcnt(0)
	s_addc_u32 s21, s21, 0
	s_addk_i32 s23, 0x800
	s_mov_b64 s[26:27], 0xa0000
	v_pk_add_f32 v[132:133], v[22:23], v[146:147]
	s_cmp_eq_u32 s20, 0x1000000
	v_lshl_add_u64 v[134:135], v[134:135], 0, s[26:27]
	s_cbranch_scc1 .LBB0_103
.LBB0_101:
	s_and_b32 s3, s23, 0x800
	s_lshl_b32 s3, s3, 2
	s_add_i32 s3, s3, 0
	v_add_u32_e32 v20, s3, v25
	s_cmp_eq_u32 s20, 0xf00000
	ds_write_b128 v20, v[0:3]
	s_cbranch_scc1 .LBB0_100
	global_load_dwordx2 v[2:3], v[134:135], off
	s_branch .LBB0_100

; __device__ __forceinline__ void xcd_barrier(const XcdBarrier& b) {
;     asm volatile("s_waitcnt vmcnt(0)" ::: "memory");
;     __syncthreads();
;     if (threadIdx.x == 0) {
;         unsigned* bar = b.bar;
;         __builtin_amdgcn_s_waitcnt(0);
;         unsigned nloc = b.st[0], nx = b.st[1];
;         if (nloc == 0u) { xcd_barrier_complete(bar, b.x, nloc, nx); b.st[0] = nloc; b.st[1] = nx; }
.Lxcd_barrier_entry:
	s_waitcnt vmcnt(0)
	s_waitcnt vmcnt(0) lgkmcnt(0)
	s_barrier
	s_mov_b64 s[0:1], exec
	v_readlane_b32 s2, v251, 2
	v_readlane_b32 s3, v251, 3
	s_and_b64 s[2:3], s[0:1], s[2:3]
	s_mov_b64 exec, s[2:3]
	s_cbranch_execz .LBB0_365
	s_add_i32 s8, 0, 0x20000
	v_mov_b32_e32 v0, s8
	s_waitcnt vmcnt(0) expcnt(0) lgkmcnt(0)
	ds_read_b32 v2, v0
	v_readlane_b32 s2, v252, 52
	s_waitcnt lgkmcnt(0)
	v_cmp_ne_u32_e32 vcc, 0, v2
	v_mov_b32_e32 v0, s2
	ds_read_b32 v0, v0
	s_cbranch_vccnz .LBB0_326
	s_mov_b32 s9, 1
	s_branch .LBB0_314

; __global__ void __launch_bounds__(512, 2) fwd(Args a_unused) {
;     ...
;         if (ph == 0) grid.sync();
;         else xcd_barrier(xbar);
.LBB0_366:
	s_and_b64 vcc, exec, s[4:5]
	s_cbranch_vccz .LBB0_16
	s_branch .Lxcd_barrier_entry
